# diff-attention main loop: K/V LDS-DMA loads of each step issued at the top of the step (ring slots already free) instead of the last three MFMA gaps
# baseline (speedup 1.0000x reference)
.LBB0_494:
	s_lshl_b32 s6, s6, 1
	v_add_u32_e32 v231, s6, v252
	s_add_i32 m0, s38, s31
	v_lshl_add_u64 v[198:199], s[2:3], 0, v[200:201]
	v_lshl_add_u64 v[198:199], v[198:199], 0, s[84:85]
	global_load_lds_dwordx4 v[198:199], off
	s_lshl_b32 s41, s26, 1
	s_add_i32 m0, s41, s34
	v_lshl_add_u64 v[196:197], s[2:3], 0, v[202:203]
	v_lshl_add_u64 v[198:199], v[196:197], 0, s[86:87]
	global_load_lds_dwordx4 v[198:199], off
	s_add_i32 m0, m0, 0x2000
	v_lshl_add_u64 v[198:199], v[196:197], 0, s[88:89]
	global_load_lds_dwordx4 v[198:199], off
	ds_read_b64_tr_b16 v[196:197], v231 offset:24576
	ds_read_b64_tr_b16 v[198:199], v231 offset:25088
	s_waitcnt lgkmcnt(9)
	v_mfma_f32_32x32x16_bf16 v[116:131], v[192:195], v[160:163], 0
	v_add_f32_e32 v100, v84, v85
	v_add_f32_e32 v100, v86, v100
	v_add_f32_e32 v100, v87, v100
	v_add_f32_e32 v100, v88, v100
	v_add_f32_e32 v132, v89, v100
	v_cvt_pk_bf16_f32 v144, v84, v85
	v_cvt_pk_bf16_f32 v145, v86, v87
	ds_read_b64_tr_b16 v[84:85], v231 offset:28672
	ds_read_b64_tr_b16 v[86:87], v231 offset:29184
	s_waitcnt lgkmcnt(10)
	v_mfma_f32_32x32x16_bf16 v[100:115], v[188:191], v[160:163], 0
	v_add_f32_e32 v132, v90, v132
	v_add_f32_e32 v132, v91, v132
	v_add_f32_e32 v132, v92, v132
	v_add_f32_e32 v132, v93, v132
	v_cvt_pk_bf16_f32 v146, v88, v89
	v_cvt_pk_bf16_f32 v147, v90, v91
	ds_read_b64_tr_b16 v[88:89], v231 offset:32768
	ds_read_b64_tr_b16 v[90:91], v231 offset:33280
	s_waitcnt lgkmcnt(11)
	v_mfma_f32_32x32x16_bf16 v[116:131], v[184:187], v[156:159], v[116:131]
	v_add_f32_e32 v132, v94, v132
	v_add_f32_e32 v132, v95, v132
	v_add_f32_e32 v132, v96, v132
	v_add_f32_e32 v132, v97, v132
	v_cvt_pk_bf16_f32 v140, v92, v93
	v_cvt_pk_bf16_f32 v141, v94, v95
	ds_read_b64_tr_b16 v[92:93], v231 offset:36864
	ds_read_b64_tr_b16 v[94:95], v231 offset:37376
	s_waitcnt lgkmcnt(12)
	v_mfma_f32_32x32x16_bf16 v[100:115], v[180:183], v[156:159], v[100:115]
	v_add_f32_e32 v132, v98, v132
	v_add_f32_e32 v132, v99, v132
	v_add_f32_e32 v132, v68, v132
	v_add_f32_e32 v132, v69, v132
	v_cvt_pk_bf16_f32 v142, v96, v97
	v_cvt_pk_bf16_f32 v143, v98, v99
	ds_read_b64_tr_b16 v[96:97], v231 offset:25600
	ds_read_b64_tr_b16 v[98:99], v231 offset:26112
	s_waitcnt lgkmcnt(13)
	v_mfma_f32_32x32x16_bf16 v[116:131], v[176:179], v[152:155], v[116:131]
	v_add_f32_e32 v132, v70, v132
	v_add_f32_e32 v132, v71, v132
	v_add_f32_e32 v132, v72, v132
	v_add_f32_e32 v132, v73, v132
	v_cvt_pk_bf16_f32 v136, v68, v69
	v_cvt_pk_bf16_f32 v137, v70, v71
	ds_read_b64_tr_b16 v[68:69], v231 offset:29696
	ds_read_b64_tr_b16 v[70:71], v231 offset:30208
	s_waitcnt lgkmcnt(14)
	v_mfma_f32_32x32x16_bf16 v[100:115], v[172:175], v[152:155], v[100:115]
	v_add_f32_e32 v132, v74, v132
	v_add_f32_e32 v132, v75, v132
	v_add_f32_e32 v132, v76, v132
	v_add_f32_e32 v132, v77, v132
	v_cvt_pk_bf16_f32 v138, v72, v73
	v_cvt_pk_bf16_f32 v139, v74, v75
	ds_read_b64_tr_b16 v[72:73], v231 offset:33792
	ds_read_b64_tr_b16 v[74:75], v231 offset:34304
	s_waitcnt lgkmcnt(14)
	v_mfma_f32_32x32x16_bf16 v[116:131], v[168:171], v[148:151], v[116:131]
	v_add_f32_e32 v132, v78, v132
	v_add_f32_e32 v132, v79, v132
	v_add_f32_e32 v132, v80, v132
	v_add_f32_e32 v168, v81, v132
	v_cvt_pk_bf16_f32 v132, v76, v77
	v_cvt_pk_bf16_f32 v133, v78, v79
	ds_read_b64_tr_b16 v[76:77], v231 offset:37888
	ds_read_b64_tr_b16 v[78:79], v231 offset:38400
	v_mfma_f32_32x32x16_bf16 v[100:115], v[164:167], v[148:151], v[100:115]
	v_add_f32_e32 v134, v82, v168
	v_add_f32_e32 v134, v83, v134
	v_add_f32_e32 v164, 0, v134
	v_cvt_pk_bf16_f32 v134, v80, v81
	v_cvt_pk_bf16_f32 v135, v82, v83
	v_cndmask_b32_e64 v80, 0, 1, s[4:5]
	v_add_f32_e32 v192, v229, v164
	v_cmp_ne_u32_e64 s[10:11], 1, v80
	s_andn2_b64 vcc, exec, s[4:5]
	s_mov_b64 s[6:7], 0
	s_cbranch_vccz .LBB0_502
.LBB0_495:
	s_waitcnt lgkmcnt(14)
	v_mfma_f32_32x32x16_bf16 v[52:67], v[144:147], v[196:199], v[52:67]
	v_exp_f32_e32 v116, v116
	v_exp_f32_e32 v117, v117
	ds_read_b64_tr_b16 v[80:81], v231 offset:26624
	ds_read_b64_tr_b16 v[82:83], v231 offset:27136
	s_waitcnt lgkmcnt(14)
	v_mfma_f32_32x32x16_bf16 v[36:51], v[144:147], v[84:87], v[36:51]
	v_exp_f32_e32 v118, v118
	v_exp_f32_e32 v119, v119
	ds_read_b64_tr_b16 v[84:85], v231 offset:30720
	ds_read_b64_tr_b16 v[86:87], v231 offset:31232
	s_waitcnt lgkmcnt(14)
	v_mfma_f32_32x32x16_bf16 v[20:35], v[144:147], v[88:91], v[20:35]
	v_exp_f32_e32 v120, v120
	v_exp_f32_e32 v121, v121
	ds_read_b64_tr_b16 v[88:89], v231 offset:34816
	ds_read_b64_tr_b16 v[90:91], v231 offset:35328
	s_waitcnt lgkmcnt(14)
	v_mfma_f32_32x32x16_bf16 v[4:19], v[144:147], v[92:95], v[4:19]
	v_exp_f32_e32 v122, v122
	v_exp_f32_e32 v123, v123
	ds_read_b64_tr_b16 v[92:93], v231 offset:38912
	ds_read_b64_tr_b16 v[94:95], v231 offset:39424
	s_waitcnt lgkmcnt(14)
	v_mfma_f32_32x32x16_bf16 v[52:67], v[140:143], v[96:99], v[52:67]
	v_exp_f32_e32 v124, v124
	v_exp_f32_e32 v125, v125
	ds_read_b64_tr_b16 v[96:97], v231 offset:27648
	ds_read_b64_tr_b16 v[98:99], v231 offset:28160
	s_waitcnt lgkmcnt(14)
	v_mfma_f32_32x32x16_bf16 v[36:51], v[140:143], v[68:71], v[36:51]
	v_exp_f32_e32 v126, v126
	v_exp_f32_e32 v127, v127
	ds_read_b64_tr_b16 v[188:189], v231 offset:31744
	ds_read_b64_tr_b16 v[190:191], v231 offset:32256
	s_waitcnt lgkmcnt(14)
	v_mfma_f32_32x32x16_bf16 v[20:35], v[140:143], v[72:75], v[20:35]
	v_exp_f32_e32 v128, v128
	v_exp_f32_e32 v129, v129
	ds_read_b64_tr_b16 v[206:207], v231 offset:35840
	ds_read_b64_tr_b16 v[208:209], v231 offset:36352
	s_waitcnt lgkmcnt(14)
	v_mfma_f32_32x32x16_bf16 v[4:19], v[140:143], v[76:79], v[4:19]
	v_exp_f32_e32 v130, v130
	v_exp_f32_e32 v131, v131
	ds_read_b64_tr_b16 v[76:77], v231 offset:39936
	ds_read_b64_tr_b16 v[78:79], v231 offset:40448
	s_waitcnt lgkmcnt(14)
	v_mfma_f32_32x32x16_bf16 v[52:67], v[136:139], v[80:83], v[52:67]
	v_exp_f32_e32 v100, v100
	v_exp_f32_e32 v101, v101
	v_add_u32_e32 v80, s26, v251
	ds_read_b128 v[72:75], v80
	ds_read_b128 v[68:71], v80 offset:512
	s_waitcnt lgkmcnt(14)
	v_mfma_f32_32x32x16_bf16 v[36:51], v[136:139], v[84:87], v[36:51]
	v_exp_f32_e32 v102, v102
	v_exp_f32_e32 v103, v103
	ds_read_b128 v[184:187], v80 offset:2048
	ds_read_b128 v[180:183], v80 offset:2560
	s_waitcnt lgkmcnt(14)
	v_mfma_f32_32x32x16_bf16 v[20:35], v[136:139], v[88:91], v[20:35]
	v_exp_f32_e32 v104, v104
	v_exp_f32_e32 v105, v105
	ds_read_b128 v[176:179], v80 offset:4096
	ds_read_b128 v[172:175], v80 offset:4608
	s_waitcnt lgkmcnt(14)
	v_mfma_f32_32x32x16_bf16 v[4:19], v[136:139], v[92:95], v[4:19]
	v_exp_f32_e32 v106, v106
	v_exp_f32_e32 v107, v107
	ds_read_b128 v[168:171], v80 offset:6144
	ds_read_b128 v[164:167], v80 offset:6656
	s_waitcnt lgkmcnt(14)
	v_mfma_f32_32x32x16_bf16 v[52:67], v[132:135], v[96:99], v[52:67]
	v_exp_f32_e32 v108, v108
	v_exp_f32_e32 v109, v109
	s_waitcnt lgkmcnt(12)
	v_mfma_f32_32x32x16_bf16 v[36:51], v[132:135], v[188:191], v[36:51]
	v_exp_f32_e32 v110, v110
	v_exp_f32_e32 v111, v111
	s_waitcnt lgkmcnt(10)
	v_mfma_f32_32x32x16_bf16 v[20:35], v[132:135], v[206:209], v[20:35]
	v_exp_f32_e32 v112, v112
	v_exp_f32_e32 v113, v113
	s_waitcnt lgkmcnt(8)
	v_mfma_f32_32x32x16_bf16 v[4:19], v[132:135], v[76:79], v[4:19]
	v_exp_f32_e32 v114, v114
	v_exp_f32_e32 v115, v115
	s_waitcnt vmcnt(3) lgkmcnt(0)
	s_barrier
	s_andn2_b64 vcc, exec, s[6:7]
	s_cbranch_vccnz .LBB0_497
	s_waitcnt lgkmcnt(0)
	v_add_u32_e32 v88, s29, v204
	ds_read_b128 v[76:79], v88 offset:96
	ds_read_b128 v[80:83], v88 offset:64
	ds_read_b128 v[84:87], v88 offset:32
	ds_read_b128 v[88:91], v88
	s_waitcnt lgkmcnt(3)
	v_pk_mul_f32 v[64:65], v[64:65], v[76:77]
	s_waitcnt lgkmcnt(2)
	v_pk_mul_f32 v[60:61], v[60:61], v[80:81]
	s_waitcnt lgkmcnt(1)
	v_pk_mul_f32 v[56:57], v[56:57], v[84:85]
	v_pk_mul_f32 v[66:67], v[66:67], v[78:79]
	v_pk_mul_f32 v[62:63], v[62:63], v[82:83]
	v_pk_mul_f32 v[58:59], v[58:59], v[86:87]
	s_waitcnt lgkmcnt(0)
	v_pk_mul_f32 v[54:55], v[54:55], v[90:91]
	v_pk_mul_f32 v[52:53], v[52:53], v[88:89]
	v_pk_mul_f32 v[48:49], v[48:49], v[76:77]
	v_pk_mul_f32 v[44:45], v[44:45], v[80:81]
	v_pk_mul_f32 v[40:41], v[40:41], v[84:85]
	v_pk_mul_f32 v[50:51], v[50:51], v[78:79]
	v_pk_mul_f32 v[46:47], v[46:47], v[82:83]
	v_pk_mul_f32 v[42:43], v[42:43], v[86:87]
	v_pk_mul_f32 v[38:39], v[38:39], v[90:91]
	v_pk_mul_f32 v[36:37], v[36:37], v[88:89]
	v_pk_mul_f32 v[32:33], v[32:33], v[76:77]
	v_pk_mul_f32 v[28:29], v[28:29], v[80:81]
	v_pk_mul_f32 v[24:25], v[24:25], v[84:85]
	v_pk_mul_f32 v[34:35], v[34:35], v[78:79]
	v_pk_mul_f32 v[30:31], v[30:31], v[82:83]
	v_pk_mul_f32 v[26:27], v[26:27], v[86:87]
	v_pk_mul_f32 v[22:23], v[22:23], v[90:91]
	v_pk_mul_f32 v[20:21], v[20:21], v[88:89]
	v_pk_mul_f32 v[16:17], v[16:17], v[76:77]
	v_pk_mul_f32 v[12:13], v[12:13], v[80:81]
	v_pk_mul_f32 v[8:9], v[8:9], v[84:85]
	v_pk_mul_f32 v[18:19], v[18:19], v[78:79]
	v_pk_mul_f32 v[14:15], v[14:15], v[82:83]
	v_pk_mul_f32 v[10:11], v[10:11], v[86:87]
	v_pk_mul_f32 v[6:7], v[6:7], v[90:91]
	v_pk_mul_f32 v[4:5], v[4:5], v[88:89]
.LBB0_497:
	s_lshl_b32 s6, s38, 1
	v_add_u32_e32 v193, s6, v252
	s_add_i32 s12, s26, 0x2000
	s_cmpk_lg_i32 s26, 0x4000
	s_cselect_b32 s12, s12, 0
	s_add_i32 m0, s26, s31
	v_lshl_add_u64 v[190:191], s[2:3], 0, v[200:201]
	v_lshl_add_u64 v[190:191], v[190:191], 0, s[90:91]
	global_load_lds_dwordx4 v[190:191], off
	s_lshl_b32 s12, s12, 1
	s_add_i32 m0, s12, s34
	v_lshl_add_u64 v[188:189], s[2:3], 0, v[202:203]
	v_lshl_add_u64 v[190:191], v[188:189], 0, s[92:93]
	global_load_lds_dwordx4 v[190:191], off
	s_add_i32 m0, m0, 0x2000
	v_lshl_add_u64 v[190:191], v[188:189], 0, s[94:95]
	global_load_lds_dwordx4 v[190:191], off
	ds_read_b64_tr_b16 v[188:189], v193 offset:24576
	ds_read_b64_tr_b16 v[190:191], v193 offset:25088
	s_waitcnt lgkmcnt(9)
	v_mfma_f32_32x32x16_bf16 v[84:99], v[72:75], v[160:163], 0
	v_add_f32_e32 v76, v116, v117
	v_add_f32_e32 v72, v118, v76
	v_add_f32_e32 v72, v119, v72
	v_add_f32_e32 v72, v120, v72
	v_add_f32_e32 v132, v121, v72
	v_cvt_pk_bf16_f32 v144, v116, v117
	v_cvt_pk_bf16_f32 v145, v118, v119
	ds_read_b64_tr_b16 v[116:117], v193 offset:28672
	ds_read_b64_tr_b16 v[118:119], v193 offset:29184
	s_waitcnt lgkmcnt(10)
	v_mfma_f32_32x32x16_bf16 v[68:83], v[68:71], v[160:163], 0
	v_add_f32_e32 v132, v122, v132
	v_add_f32_e32 v132, v123, v132
	v_add_f32_e32 v132, v124, v132
	v_add_f32_e32 v132, v125, v132
	v_cvt_pk_bf16_f32 v146, v120, v121
	v_cvt_pk_bf16_f32 v147, v122, v123
	ds_read_b64_tr_b16 v[120:121], v193 offset:32768
	ds_read_b64_tr_b16 v[122:123], v193 offset:33280
	s_waitcnt lgkmcnt(11)
	v_mfma_f32_32x32x16_bf16 v[84:99], v[184:187], v[156:159], v[84:99]
	v_add_f32_e32 v132, v126, v132
	v_add_f32_e32 v132, v127, v132
	v_add_f32_e32 v132, v128, v132
	v_add_f32_e32 v132, v129, v132
	v_cvt_pk_bf16_f32 v140, v124, v125
	v_cvt_pk_bf16_f32 v141, v126, v127
	ds_read_b64_tr_b16 v[124:125], v193 offset:36864
	ds_read_b64_tr_b16 v[126:127], v193 offset:37376
	s_waitcnt lgkmcnt(12)
	v_mfma_f32_32x32x16_bf16 v[68:83], v[180:183], v[156:159], v[68:83]
	v_add_f32_e32 v132, v130, v132
	v_add_f32_e32 v132, v131, v132
	v_add_f32_e32 v132, v100, v132
	v_add_f32_e32 v132, v101, v132
	v_cvt_pk_bf16_f32 v142, v128, v129
	v_cvt_pk_bf16_f32 v143, v130, v131
	ds_read_b64_tr_b16 v[128:129], v193 offset:25600
	ds_read_b64_tr_b16 v[130:131], v193 offset:26112
	s_waitcnt lgkmcnt(13)
	v_mfma_f32_32x32x16_bf16 v[84:99], v[176:179], v[152:155], v[84:99]
	v_add_f32_e32 v132, v102, v132
	v_add_f32_e32 v132, v103, v132
	v_add_f32_e32 v132, v104, v132
	v_add_f32_e32 v132, v105, v132
	v_cvt_pk_bf16_f32 v136, v100, v101
	v_cvt_pk_bf16_f32 v137, v102, v103
	ds_read_b64_tr_b16 v[100:101], v193 offset:29696
	ds_read_b64_tr_b16 v[102:103], v193 offset:30208
	s_waitcnt lgkmcnt(14)
	v_mfma_f32_32x32x16_bf16 v[68:83], v[172:175], v[152:155], v[68:83]
	v_add_f32_e32 v132, v106, v132
	v_add_f32_e32 v132, v107, v132
	v_add_f32_e32 v132, v108, v132
	v_add_f32_e32 v132, v109, v132
	v_cvt_pk_bf16_f32 v138, v104, v105
	v_cvt_pk_bf16_f32 v139, v106, v107
	ds_read_b64_tr_b16 v[104:105], v193 offset:33792
	ds_read_b64_tr_b16 v[106:107], v193 offset:34304
	s_waitcnt lgkmcnt(14)
	v_mfma_f32_32x32x16_bf16 v[84:99], v[168:171], v[148:151], v[84:99]
	v_add_f32_e32 v132, v110, v132
	v_add_f32_e32 v132, v111, v132
	v_add_f32_e32 v132, v112, v132
	v_add_f32_e32 v168, v113, v132
	v_cvt_pk_bf16_f32 v132, v108, v109
	v_cvt_pk_bf16_f32 v133, v110, v111
	ds_read_b64_tr_b16 v[108:109], v193 offset:37888
	ds_read_b64_tr_b16 v[110:111], v193 offset:38400
	v_mfma_f32_32x32x16_bf16 v[68:83], v[164:167], v[148:151], v[68:83]
	v_add_f32_e32 v134, v114, v168
	v_add_f32_e32 v134, v115, v134
	v_add_f32_e32 v164, 0, v134
	v_cvt_pk_bf16_f32 v134, v112, v113
	v_cvt_pk_bf16_f32 v135, v114, v115
	s_nop 0
	v_add_f32_e32 v229, v192, v164
	s_and_b64 vcc, exec, s[10:11]
	s_mov_b64 s[6:7], 0
	s_cbranch_vccz .LBB0_505
.LBB0_498:
	s_add_i32 s12, s26, 0x2000
	s_cmpk_lg_i32 s26, 0x4000
	s_cselect_b32 s38, s12, 0
	s_waitcnt lgkmcnt(14)
	v_mfma_f32_32x32x16_bf16 v[52:67], v[144:147], v[188:191], v[52:67]
	v_exp_f32_e32 v84, v84
	v_exp_f32_e32 v85, v85
	ds_read_b64_tr_b16 v[112:113], v193 offset:26624
	ds_read_b64_tr_b16 v[114:115], v193 offset:27136
	s_waitcnt lgkmcnt(14)
	v_mfma_f32_32x32x16_bf16 v[36:51], v[144:147], v[116:119], v[36:51]
	v_exp_f32_e32 v86, v86
	v_exp_f32_e32 v87, v87
	ds_read_b64_tr_b16 v[116:117], v193 offset:30720
	ds_read_b64_tr_b16 v[118:119], v193 offset:31232
	s_waitcnt lgkmcnt(14)
	v_mfma_f32_32x32x16_bf16 v[20:35], v[144:147], v[120:123], v[20:35]
	v_exp_f32_e32 v88, v88
	v_exp_f32_e32 v89, v89
	ds_read_b64_tr_b16 v[120:121], v193 offset:34816
	ds_read_b64_tr_b16 v[122:123], v193 offset:35328
	s_waitcnt lgkmcnt(14)
	v_mfma_f32_32x32x16_bf16 v[4:19], v[144:147], v[124:127], v[4:19]
	v_exp_f32_e32 v90, v90
	v_exp_f32_e32 v91, v91
	ds_read_b64_tr_b16 v[124:125], v193 offset:38912
	ds_read_b64_tr_b16 v[126:127], v193 offset:39424
	s_waitcnt lgkmcnt(14)
	v_mfma_f32_32x32x16_bf16 v[52:67], v[140:143], v[128:131], v[52:67]
	v_exp_f32_e32 v92, v92
	v_exp_f32_e32 v93, v93
	ds_read_b64_tr_b16 v[128:129], v193 offset:27648
	ds_read_b64_tr_b16 v[130:131], v193 offset:28160
	s_waitcnt lgkmcnt(14)
	v_mfma_f32_32x32x16_bf16 v[36:51], v[140:143], v[100:103], v[36:51]
	v_exp_f32_e32 v94, v94
	v_exp_f32_e32 v95, v95
	ds_read_b64_tr_b16 v[100:101], v193 offset:31744
	ds_read_b64_tr_b16 v[102:103], v193 offset:32256
	s_waitcnt lgkmcnt(14)
	v_mfma_f32_32x32x16_bf16 v[20:35], v[140:143], v[104:107], v[20:35]
	v_exp_f32_e32 v96, v96
	v_exp_f32_e32 v97, v97
	ds_read_b64_tr_b16 v[104:105], v193 offset:35840
	ds_read_b64_tr_b16 v[106:107], v193 offset:36352
	s_waitcnt lgkmcnt(14)
	v_mfma_f32_32x32x16_bf16 v[4:19], v[140:143], v[108:111], v[4:19]
	v_exp_f32_e32 v98, v98
	v_exp_f32_e32 v99, v99
	ds_read_b64_tr_b16 v[108:109], v193 offset:39936
	ds_read_b64_tr_b16 v[110:111], v193 offset:40448
	s_waitcnt lgkmcnt(14)
	v_mfma_f32_32x32x16_bf16 v[52:67], v[136:139], v[112:115], v[52:67]
	v_exp_f32_e32 v68, v68
	v_exp_f32_e32 v69, v69
	v_add_u32_e32 v112, s38, v251
	ds_read_b128 v[192:195], v112
	ds_read_b128 v[188:191], v112 offset:512
	s_waitcnt lgkmcnt(14)
	v_mfma_f32_32x32x16_bf16 v[36:51], v[136:139], v[116:119], v[36:51]
	v_exp_f32_e32 v70, v70
	v_exp_f32_e32 v71, v71
	ds_read_b128 v[184:187], v112 offset:2048
	ds_read_b128 v[180:183], v112 offset:2560
	s_waitcnt lgkmcnt(14)
	v_mfma_f32_32x32x16_bf16 v[20:35], v[136:139], v[120:123], v[20:35]
	v_exp_f32_e32 v72, v72
	v_exp_f32_e32 v73, v73
	ds_read_b128 v[176:179], v112 offset:4096
	ds_read_b128 v[172:175], v112 offset:4608
	s_waitcnt lgkmcnt(14)
	v_mfma_f32_32x32x16_bf16 v[4:19], v[136:139], v[124:127], v[4:19]
	v_exp_f32_e32 v74, v74
	v_exp_f32_e32 v75, v75
	ds_read_b128 v[168:171], v112 offset:6144
	ds_read_b128 v[164:167], v112 offset:6656
	s_waitcnt lgkmcnt(14)
	v_mfma_f32_32x32x16_bf16 v[52:67], v[132:135], v[128:131], v[52:67]
	v_exp_f32_e32 v76, v76
	v_exp_f32_e32 v77, v77
	s_waitcnt lgkmcnt(12)
	v_mfma_f32_32x32x16_bf16 v[36:51], v[132:135], v[100:103], v[36:51]
	v_exp_f32_e32 v78, v78
	v_exp_f32_e32 v79, v79
	s_waitcnt lgkmcnt(10)
	v_mfma_f32_32x32x16_bf16 v[20:35], v[132:135], v[104:107], v[20:35]
	v_exp_f32_e32 v80, v80
	v_exp_f32_e32 v81, v81
	s_waitcnt lgkmcnt(8)
	v_mfma_f32_32x32x16_bf16 v[4:19], v[132:135], v[108:111], v[4:19]
	v_exp_f32_e32 v82, v82
	v_exp_f32_e32 v83, v83
	s_waitcnt vmcnt(3) lgkmcnt(0)
	s_barrier
	s_andn2_b64 vcc, exec, s[6:7]
	s_cbranch_vccnz .LBB0_500
	s_waitcnt lgkmcnt(0)
	v_add_u32_e32 v112, s29, v204
	ds_read_b128 v[100:103], v112 offset:96
	ds_read_b128 v[104:107], v112 offset:64
	ds_read_b128 v[108:111], v112 offset:32
	ds_read_b128 v[112:115], v112
	s_waitcnt lgkmcnt(3)
	v_pk_mul_f32 v[64:65], v[64:65], v[100:101]
	s_waitcnt lgkmcnt(2)
	v_pk_mul_f32 v[60:61], v[60:61], v[104:105]
	s_waitcnt lgkmcnt(1)
	v_pk_mul_f32 v[56:57], v[56:57], v[108:109]
	v_pk_mul_f32 v[66:67], v[66:67], v[102:103]
	v_pk_mul_f32 v[62:63], v[62:63], v[106:107]
	v_pk_mul_f32 v[58:59], v[58:59], v[110:111]
	s_waitcnt lgkmcnt(0)
	v_pk_mul_f32 v[54:55], v[54:55], v[114:115]
	v_pk_mul_f32 v[52:53], v[52:53], v[112:113]
	v_pk_mul_f32 v[48:49], v[48:49], v[100:101]
	v_pk_mul_f32 v[44:45], v[44:45], v[104:105]
	v_pk_mul_f32 v[40:41], v[40:41], v[108:109]
	v_pk_mul_f32 v[50:51], v[50:51], v[102:103]
	v_pk_mul_f32 v[46:47], v[46:47], v[106:107]
	v_pk_mul_f32 v[42:43], v[42:43], v[110:111]
	v_pk_mul_f32 v[38:39], v[38:39], v[114:115]
	v_pk_mul_f32 v[36:37], v[36:37], v[112:113]
	v_pk_mul_f32 v[32:33], v[32:33], v[100:101]
	v_pk_mul_f32 v[28:29], v[28:29], v[104:105]
	v_pk_mul_f32 v[24:25], v[24:25], v[108:109]
	v_pk_mul_f32 v[34:35], v[34:35], v[102:103]
	v_pk_mul_f32 v[30:31], v[30:31], v[106:107]
	v_pk_mul_f32 v[26:27], v[26:27], v[110:111]
	v_pk_mul_f32 v[22:23], v[22:23], v[114:115]
	v_pk_mul_f32 v[20:21], v[20:21], v[112:113]
	v_pk_mul_f32 v[16:17], v[16:17], v[100:101]
	v_pk_mul_f32 v[12:13], v[12:13], v[104:105]
	v_pk_mul_f32 v[8:9], v[8:9], v[108:109]
	v_pk_mul_f32 v[18:19], v[18:19], v[102:103]
	v_pk_mul_f32 v[14:15], v[14:15], v[106:107]
	v_pk_mul_f32 v[10:11], v[10:11], v[110:111]
	v_pk_mul_f32 v[6:7], v[6:7], v[114:115]
	v_pk_mul_f32 v[4:5], v[4:5], v[112:113]
